# skip XCD-leader L2 writeback at 3 panel-local seams (after branch, out-proj, FFN2 gate-up) when hardware XCC id == blockIdx%8 for every WG (runtime-checked flag), else unchanged
# baseline (speedup 1.0000x reference)
_Z8mega_fwd4Args:
	s_load_dword s33, s[0:1], 0xd8
	s_load_dwordx2 s[82:83], s[0:1], 0xd0
	s_mov_b64 s[80:81], s[0:1]
	s_add_u32 s16, s80, 0xd0
	v_and_b32_e32 v206, 0x3ff, v0
	s_mov_b32 s78, s2
	s_mov_b32 s100, 1
	s_mov_b32 s101, 1
	s_addc_u32 s17, s81, 0
	v_cmp_gt_u32_e32 vcc, 4, v206
	s_and_saveexec_b64 s[0:1], vcc
	v_lshl_add_u32 v1, v206, 2, 0
	v_add_u32_e32 v1, 0x23fc0, v1
	v_mov_b32_e32 v2, 0
	ds_write_b32 v1, v2
	s_or_b64 exec, exec, s[0:1]
	s_load_dwordx2 s[86:87], s[80:81], 0xc8
	v_mov_b32_e32 v1, v206
	s_mov_b32 s38, 0
	s_waitcnt lgkmcnt(0)
	s_barrier
	s_add_u32 s18, s86, s38
	v_readfirstlane_b32 s0, v1
	s_addc_u32 s19, s87, 0
	s_ashr_i32 s0, s0, 6
	s_lshl_b32 s97, s78, 3
	s_add_i32 s20, s0, s97
	s_lshl_b32 s84, s82, 3
	s_mov_b32 s23, 0
	s_cmpk_gt_i32 s20, 0x2ebf
	v_and_b32_e32 v41, 63, v1
	s_cbranch_scc1 .LBB0_144
	s_load_dwordx8 s[4:11], s[80:81], 0x30
	s_load_dwordx4 s[12:15], s[80:81], 0x50
	s_lshl_b32 s1, s0, 14
	s_add_i32 s1, s1, 0
	s_add_u32 s21, s18, 0x200000
	v_lshrrev_b32_e32 v35, 3, v41
	v_and_b32_e32 v2, 7, v1
	s_addc_u32 s39, s19, 0
	v_lshlrev_b32_e32 v34, 2, v2
	v_mov_b32_e32 v37, 0
	v_lshlrev_b32_e32 v36, 4, v2
	v_lshlrev_b32_e32 v40, 3, v2
	v_mul_u32_u24_e32 v2, 0x420, v2
	v_lshlrev_b32_e32 v3, 2, v35
	s_waitcnt lgkmcnt(0)
	s_cmp_lg_u64 s[12:13], 0
	v_add3_u32 v61, s1, v2, v3
	v_lshl_add_u64 v[2:3], s[18:19], 0, v[36:37]
	s_mov_b64 s[2:3], 0x1b00000
	v_lshl_add_u64 v[38:39], s[14:15], 0, v[36:37]
	s_cselect_b64 s[14:15], -1, 0
	s_cmp_lg_u64 s[8:9], 0
	v_lshl_add_u64 v[44:45], v[2:3], 0, s[2:3]
	s_mov_b64 s[2:3], 0x1a00000
	v_lshl_add_u64 v[42:43], s[10:11], 0, v[36:37]
	s_cselect_b64 s[10:11], -1, 0
	s_cmp_lg_u64 s[4:5], 0
	v_lshl_add_u64 v[46:47], v[2:3], 0, s[2:3]
	s_mov_b64 s[2:3], 0x1280000
	v_add_u32_e32 v56, s1, v36
	s_cselect_b64 s[24:25], -1, 0
	v_lshl_add_u64 v[50:51], v[2:3], 0, s[2:3]
	s_lshl_b32 s1, s78, 8
	s_lshl_b32 s2, s0, 5
	s_add_i32 s40, s1, s2
	s_lshl_b32 s1, s78, 4
	s_lshl_b32 s2, s0, 1
	s_add_i32 s42, s1, s2
	s_lshl_b32 s1, s78, 5
	s_lshl_b32 s0, s0, 2
	v_mul_u32_u24_e32 v57, 0x84, v35
	v_or_b32_e32 v58, 8, v35
	v_or_b32_e32 v59, 16, v35
	v_or_b32_e32 v60, 24, v35
	v_lshl_add_u64 v[48:49], s[6:7], 0, v[36:37]
	s_lshl_b32 s41, s82, 8
	s_lshl_b32 s43, s82, 4
	s_add_i32 s44, s1, s0
	s_lshl_b32 s45, s82, 5
	s_movk_i32 s46, 0xd580
	v_cndmask_b32_e64 v62, 0, 1, s[14:15]
	s_mov_b32 s47, 0x1a00000
	s_movk_i32 s48, 0xc00
	s_mov_b64 s[26:27], 0x1a80
	s_movk_i32 s49, 0x4280
	s_movk_i32 s50, 0xfd00
	s_movk_i32 s51, 0x2a0
	s_mov_b32 s52, 0x2940000
	s_movk_i32 s53, 0x2c00
	s_mov_b32 s54, s20
	s_branch .LBB0_6

.LBB0_179:
	s_add_u32 s0, s86, 0x100000
	s_addc_u32 s1, s87, 0
	v_writelane_b32 v252, s0, 1
	s_mov_b32 s2, 0
	v_cmp_eq_u32_e64 s[92:93], 0, v206
	v_writelane_b32 v252, s1, 2
	s_getreg_b32 s0, hwreg(HW_REG_XCC_ID, 0, 4)
	s_and_b32 s79, s0, 15
	s_and_saveexec_b64 s[0:1], s[92:93]
	s_cbranch_execz .LBB0_182
	s_mov_b64 s[4:5], exec
	v_mbcnt_lo_u32_b32 v0, s4, 0
	v_mbcnt_hi_u32_b32 v0, s5, v0
	v_cmp_eq_u32_e32 vcc, 0, v0
	s_and_b64 s[6:7], exec, vcc
	s_mov_b64 exec, s[6:7]
	s_cbranch_execz .LBB0_182
	s_bcnt1_i32_b64 s4, s[4:5]
	s_lshl_b32 s3, s79, 8
	v_mov_b32_e32 v1, s4
	v_readlane_b32 s4, v252, 1
	v_mov_b32_e32 v0, s3
	v_readlane_b32 s5, v252, 2
	s_nop 4
	s_and_b32 s6, s78, 7
	s_cmp_eq_u32 s6, s79
	s_cbranch_scc1 .Lxcd_canon
	v_mov_b32_e32 v2, 0
	global_atomic_or v2, v1, s[4:5]
.Lxcd_canon:
	global_atomic_add v0, v1, s[4:5] offset:1024

.LBB0_234:
	s_or_b64 exec, exec, s[0:1]
	s_cmpk_lt_i32 s78, 0xb0
	s_cselect_b64 s[0:1], -1, 0
	v_writelane_b32 v252, s0, 3
	s_cmpk_lt_i32 s78, 0xb00
	s_load_dwordx16 s[8:23], s[80:81], 0x30
	v_writelane_b32 v252, s1, 4
	s_cselect_b64 s[0:1], -1, 0
	v_writelane_b32 v252, s0, 5
	s_ashr_i32 s70, s78, 31
	s_ashr_i32 s71, s82, 31
	v_writelane_b32 v252, s1, 6
	s_lshr_b32 s0, s70, 29
	s_add_i32 s0, s78, s0
	s_ashr_i32 s3, s0, 3
	s_and_b32 s0, s0, -8
	s_sub_i32 s4, s78, s0
	s_cmp_lt_i32 s78, 64
	s_cselect_b64 s[0:1], -1, 0
	v_writelane_b32 v252, s0, 7
	s_cmpk_lt_i32 s78, 0x200
	s_movk_i32 s75, 0x161
	v_writelane_b32 v252, s1, 8
	s_cselect_b64 s[0:1], -1, 0
	s_lshl_b32 s2, s4, 6
	v_writelane_b32 v252, s0, 9
	s_cmpk_lt_i32 s78, 0x780
	v_mov_b32_e32 v149, 0
	v_writelane_b32 v252, s1, 10
	s_cselect_b64 s[0:1], -1, 0
	v_writelane_b32 v252, s0, 11
	s_cmpk_lt_i32 s78, 0x100
	v_mov_b32_e32 v207, 0x358637bd
	v_writelane_b32 v252, s1, 12
	s_cselect_b64 s[0:1], -1, 0
	s_lshl_b32 s5, s4, 5
	s_add_i32 s6, s78, 0xffffff80
	s_cmpk_eq_i32 s82, 0x100
	v_writelane_b32 v252, s0, 13
	s_cselect_b64 s[68:69], -1, 0
	v_mov_b32_e32 v211, 1
	v_writelane_b32 v252, s1, 14
	s_and_b64 s[0:1], s[68:69], exec
	s_cselect_b32 s24, s6, s78
	s_cselect_b32 s72, 0x80, s82
	s_cmpk_lt_u32 s24, 0x110
	s_cselect_b64 s[0:1], -1, 0
	v_writelane_b32 v252, s0, 15
	s_waitcnt lgkmcnt(0)
	s_cmp_lg_u64 s[16:17], 0
	v_mbcnt_hi_u32_b32 v210, -1, v36
	v_writelane_b32 v252, s1, 16
	s_cselect_b64 s[0:1], -1, 0
	v_writelane_b32 v252, s0, 17
	s_cmp_lg_u64 s[12:13], 0
	v_mov_b64_e32 v[250:251], 0x200
	v_writelane_b32 v252, s1, 18
	s_cselect_b64 s[0:1], -1, 0
	v_writelane_b32 v252, s0, 19
	v_mov_b32_e32 v216, 0xff800000
	s_movk_i32 s31, 0x1600
	v_writelane_b32 v252, s1, 20
	v_writelane_b32 v252, s8, 21
	s_cmp_lg_u64 s[8:9], 0
	s_cselect_b64 s[0:1], -1, 0
	v_writelane_b32 v252, s9, 22
	v_writelane_b32 v252, s10, 23
	v_writelane_b32 v252, s11, 24
	v_writelane_b32 v252, s12, 25
	v_writelane_b32 v252, s13, 26
	v_writelane_b32 v252, s14, 27
	v_writelane_b32 v252, s15, 28
	v_writelane_b32 v252, s16, 29
	v_writelane_b32 v252, s17, 30
	v_writelane_b32 v252, s18, 31
	v_writelane_b32 v252, s19, 32
	v_writelane_b32 v252, s20, 33
	v_writelane_b32 v252, s21, 34
	v_writelane_b32 v252, s22, 35
	v_writelane_b32 v252, s23, 36
	v_writelane_b32 v252, s0, 37
	s_cmpk_lt_i32 s78, 0x400
	s_mov_b32 s49, 0
	v_writelane_b32 v252, s1, 38
	s_cselect_b64 s[0:1], -1, 0
	v_writelane_b32 v252, s0, 39
	s_lshr_b32 s73, s78, 3
	s_mov_b64 s[28:29], 0x80
	v_writelane_b32 v252, s1, 40
	s_lshl_b32 s0, s78, 1
	s_and_b32 s0, s0, 14
	s_ashr_i32 s1, s78, 7
	s_add_i32 s74, s0, s1
	s_and_b32 s0, s82, 7
	s_cmp_eq_u32 s0, 0
	s_cselect_b64 s[0:1], -1, 0
	v_writelane_b32 v252, s0, 41
	s_mov_b64 s[36:37], 0x100
	s_nop 0
	v_writelane_b32 v252, s1, 42
	s_lshr_b32 s0, s82, 3
	s_and_b32 s1, s97, 56
	s_mul_i32 s0, s1, s0
	s_add_i32 s0, s0, s78
	s_and_b32 s0, s0, -8
	s_cmp_lt_i32 s4, 0
	v_writelane_b32 v252, s0, 43
	s_mul_i32 s0, s4, 0x41
	s_cselect_b32 s6, s75, 0x160
	s_mul_i32 s1, s4, 33
	s_mul_i32 s6, s4, s6
	s_cselect_b32 s2, s0, s2
	s_movk_i32 s0, 0xf1
	s_cselect_b32 s7, s0, 0xf0
	s_cselect_b32 s1, s1, s5
	s_add_i32 s6, s6, s3
	s_mul_hi_i32 s0, s6, 0x2e8ba2e9
	s_lshr_b32 s5, s0, 31
	s_ashr_i32 s0, s0, 5
	s_add_i32 s0, s0, s5
	s_mul_i32 s5, s0, 0xb0
	s_sub_i32 s5, s6, s5
	s_lshl_b32 s8, s0, 3
	s_bfe_u32 s0, s5, 0x3001c
	s_add_i32 s6, s5, s0
	s_sext_i32_i16 s9, s6
	s_and_b32 s6, s6, 0xfff8
	s_sub_i32 s5, s5, s6
	s_sext_i32_i16 s5, s5
	s_add_i32 s12, s8, s5
	s_ashr_i32 s5, s9, 3
	s_add_i32 s2, s2, s3
	v_writelane_b32 v252, s5, 44
	s_ashr_i32 s5, s2, 31
	s_lshr_b32 s5, s5, 27
	s_add_i32 s5, s2, s5
	s_ashr_i32 s6, s5, 5
	s_and_b32 s5, s5, 0xffe0
	s_sub_i32 s5, s2, s5
	s_bfe_i32 s2, s5, 0x80000
	s_bfe_u32 s2, s2, 0x3000c
	s_add_i32 s8, s5, s2
	s_bfe_i32 s2, s8, 0x80000
	s_and_b32 s8, s8, 0xf8
	s_sub_i32 s5, s5, s8
	s_lshr_b32 s0, s9, 3
	s_lshl_b32 s6, s6, 3
	s_sext_i32_i16 s9, s2
	s_sext_i32_i8 s5, s5
	s_mul_i32 s4, s4, s7
	s_add_i32 s76, s6, s5
	s_ashr_i32 s5, s9, 3
	s_add_i32 s4, s4, s3
	v_writelane_b32 v252, s5, 45
	s_mul_hi_i32 s5, s4, 0x88888889
	s_add_i32 s5, s5, s4
	s_lshr_b32 s6, s5, 31
	s_ashr_i32 s5, s5, 6
	s_add_i32 s5, s5, s6
	s_mul_i32 s6, s5, 0x78
	s_sub_i32 s6, s4, s6
	s_bfe_i32 s4, s6, 0x80000
	s_bfe_u32 s4, s4, 0x3000c
	s_add_i32 s7, s6, s4
	s_bfe_i32 s4, s7, 0x80000
	s_and_b32 s7, s7, 0xf8
	s_sub_i32 s6, s6, s7
	s_lshl_b32 s5, s5, 3
	s_sext_i32_i16 s8, s4
	s_sext_i32_i8 s6, s6
	s_add_i32 s14, s5, s6
	s_ashr_i32 s5, s8, 3
	s_add_i32 s1, s1, s3
	v_writelane_b32 v252, s5, 46
	s_ashr_i32 s5, s1, 31
	s_lshr_b32 s3, s5, 22
	s_add_i32 s3, s1, s3
	s_ashr_i32 s6, s3, 10
	s_lshr_b32 s4, s8, 3
	s_lshl_b32 s8, s6, 3
	s_sub_i32 s6, 2, s8
	s_ashr_i32 s77, s76, 31
	s_lshr_b32 s2, s9, 3
	s_min_u32 s9, s6, 8
	s_lshl_b64 s[6:7], s[76:77], 18
	s_lshr_b32 s5, s5, 28
	v_writelane_b32 v252, s6, 47
	s_add_i32 s5, s1, s5
	s_and_b32 s3, s3, 0xfffffc00
	v_writelane_b32 v252, s7, 48
	s_ashr_i32 s6, s5, 4
	s_and_b32 s5, s5, 0xfff0
	s_sub_i32 s10, s1, s3
	s_sub_i32 s1, s1, s5
	s_bfe_i32 s5, s1, 0x80000
	s_bfe_u32 s5, s5, 0x3000c
	s_add_i32 s5, s1, s5
	s_lshl_b32 s7, s6, 3
	s_bfe_i32 s6, s5, 0x80000
	s_and_b32 s5, s5, 0xf8
	s_sub_i32 s1, s1, s5
	s_sext_i32_i16 s11, s6
	s_sext_i32_i8 s1, s1
	s_add_i32 s18, s7, s1
	s_ashr_i32 s1, s11, 3
	v_writelane_b32 v252, s1, 49
	s_mov_b32 s16, s18
	s_ashr_i32 s19, s18, 31
	v_writelane_b32 v252, s16, 50
	s_lshr_b32 s6, s11, 3
	s_bfe_i64 s[6:7], s[6:7], 0x100000
	v_writelane_b32 v252, s17, 51
	s_lshl_b64 s[16:17], s[18:19], 17
	v_writelane_b32 v252, s16, 52
	s_lshl_b64 s[6:7], s[6:7], 17
	s_ashr_i32 s13, s12, 31
	v_writelane_b32 v252, s17, 53
	v_writelane_b32 v252, s6, 54
	s_bfe_i64 s[0:1], s[0:1], 0x100000
	s_lshl_b64 s[0:1], s[0:1], 19
	v_writelane_b32 v252, s7, 55
	s_mov_b32 s6, s12
	v_writelane_b32 v252, s6, 56
	s_ashr_i32 s15, s14, 31
	s_bfe_i64 s[4:5], s[4:5], 0x100000
	v_writelane_b32 v252, s7, 57
	s_lshl_b64 s[6:7], s[12:13], 19
	v_writelane_b32 v252, s6, 58
	s_bfe_i64 s[2:3], s[2:3], 0x100000
	s_lshl_b64 s[4:5], s[4:5], 19
	v_writelane_b32 v252, s7, 59
	v_writelane_b32 v252, s0, 60
	v_writelane_b32 v253, s4, 0
	v_cvt_f32_ubyte0_e32 v1, s9
	v_writelane_b32 v252, s1, 61
	s_mov_b32 s0, s14
	v_writelane_b32 v252, s0, 62
	v_writelane_b32 v253, s5, 1
	v_cvt_f32_i32_e32 v0, s10
	v_writelane_b32 v252, s1, 63
	s_lshl_b64 s[0:1], s[14:15], 19
	s_add_u32 s0, s90, s0
	s_addc_u32 s1, s91, s1
	s_add_u32 s4, s0, 0x40000
	v_writelane_b32 v253, s0, 2
	s_addc_u32 s5, s1, 0
	v_rcp_iflag_f32_e32 v2, v1
	v_writelane_b32 v253, s1, 3
	v_writelane_b32 v253, s4, 4
	s_lshl_b64 s[0:1], s[2:3], 18
	v_mul_f32_e32 v2, v0, v2
	v_writelane_b32 v253, s5, 5
	v_writelane_b32 v253, s0, 6
	v_trunc_f32_e32 v2, v2
	v_fma_f32 v0, -v2, v1, v0
	v_writelane_b32 v253, s1, 7
	s_lshl_b64 s[0:1], s[2:3], 19
	v_writelane_b32 v253, s0, 8
	s_mov_b64 s[12:13], -1
	s_barrier
	v_readlane_b32 s4, v252, 1
	v_readlane_b32 s5, v252, 2
	v_mov_b32_e32 v4, 0
	s_nop 4
	global_load_dword v4, v4, s[4:5] sc1
	s_waitcnt vmcnt(0)
	v_readfirstlane_b32 s100, v4
	v_writelane_b32 v253, s1, 9
	s_ashr_i32 s0, s10, 30
	s_or_b32 s2, s0, 1
	s_lshl_b64 s[0:1], s[76:77], 19
	v_writelane_b32 v253, s0, 10
	s_nop 1
	v_writelane_b32 v253, s1, 11
	v_cmp_ge_f32_e64 s[0:1], |v0|, v1
	v_cvt_i32_f32_e32 v0, v2
	s_and_b64 s[0:1], s[0:1], exec
	s_cselect_b32 s0, s2, 0
	v_readfirstlane_b32 s1, v0
	s_add_i32 s0, s1, s0
	s_mul_i32 s1, s0, s9
	s_sub_i32 s1, s10, s1
	s_sext_i32_i16 s1, s1
	s_add_i32 s6, s8, s1
	s_ashr_i32 s7, s6, 31
	s_lshl_b64 s[2:3], s[6:7], 19
	v_writelane_b32 v253, s2, 12
	s_mov_b64 s[10:11], 0
	s_nop 0
	v_writelane_b32 v253, s3, 13
	s_bfe_i64 s[2:3], s[0:1], 0x100000
	s_lshl_b64 s[4:5], s[2:3], 19
	s_add_u32 s4, s90, s4
	s_addc_u32 s5, s91, s5
	s_sext_i32_i16 s0, s0
	s_mul_i32 s1, s83, s82
	v_writelane_b32 v253, s0, 14
	s_add_u32 s0, s4, 0x40000
	s_mul_i32 s34, s1, s33
	s_addc_u32 s1, s5, 0
	v_writelane_b32 v253, s0, 15
	s_nop 1
	v_writelane_b32 v253, s1, 16
	s_add_u32 s0, s4, 0x40080
	v_writelane_b32 v253, s4, 17
	s_addc_u32 s1, s5, 0
	s_lshl_b32 s33, s82, 4
	v_writelane_b32 v253, s5, 18
	v_writelane_b32 v253, s0, 19
	s_lshl_b32 s27, s82, 5
	s_nop 0
	v_writelane_b32 v253, s1, 20
	s_lshl_b64 s[0:1], s[2:3], 17
	v_writelane_b32 v253, s0, 21
	s_nop 1
	v_writelane_b32 v253, s1, 22
	s_lshl_b32 s0, s78, 4
	v_writelane_b32 v253, s0, 23
	s_lshl_b32 s0, s78, 5
	v_writelane_b32 v253, s0, 24
	s_lshl_b32 s0, s24, 14
	v_writelane_b32 v253, s0, 25
	s_lshl_b32 s0, s72, 14
	v_writelane_b32 v253, s0, 26
	v_writelane_b32 v253, s24, 27
	s_lshl_b32 s0, s24, 4
	v_writelane_b32 v253, s0, 28
	s_lshl_b32 s0, s72, 4
	v_writelane_b32 v253, s0, 29
	s_mov_b32 s0, s6
	v_writelane_b32 v253, s0, 30
	s_nop 1
	v_writelane_b32 v253, s1, 31
	s_lshl_b64 s[0:1], s[6:7], 17
	v_writelane_b32 v253, s0, 32
	s_nop 1
	v_writelane_b32 v253, s1, 33
	s_add_u32 s0, s86, 0x36c20
	v_writelane_b32 v253, s0, 34
	s_addc_u32 s0, s87, 0
	v_writelane_b32 v253, s0, 35
	s_add_u32 s0, s86, 0x200080
	v_writelane_b32 v253, s0, 36
	s_addc_u32 s0, s87, 0
	v_writelane_b32 v253, s0, 37
	s_lshl_b32 s0, s78, 7
	v_writelane_b32 v253, s0, 38
	s_lshl_b32 s0, s82, 7
	v_writelane_b32 v253, s0, 39
	s_add_u32 s0, s86, 0x7a880
	v_writelane_b32 v253, s0, 40
	s_addc_u32 s0, s87, 0
	v_writelane_b32 v253, s0, 41
	s_add_u32 s0, s78, s82
	s_addc_u32 s1, s70, s71
	v_writelane_b32 v253, s0, 42
	s_ashr_i32 s85, s84, 31
	s_nop 0
	v_writelane_b32 v253, s1, 43
	s_ashr_i32 s0, s97, 31
	v_writelane_b32 v253, s0, 44
	s_lshl_b64 s[0:1], s[84:85], 11
	v_writelane_b32 v253, s0, 45
	s_nop 1
	v_writelane_b32 v253, s1, 46
	s_add_u32 s0, s86, 0x1b600000
	s_addc_u32 s1, s87, 0
	v_writelane_b32 v253, s0, 47
	s_nop 1
	v_writelane_b32 v253, s1, 48
	s_lshl_b64 s[0:1], s[84:85], 10
	v_writelane_b32 v253, s0, 49
	s_nop 1
	v_writelane_b32 v253, s1, 50
	s_add_u32 s0, s86, 0x5600000
	s_addc_u32 s1, s87, 0
	v_writelane_b32 v253, s0, 51
	s_nop 1
	v_writelane_b32 v253, s1, 52
	s_lshl_b32 s0, s78, 8
	v_writelane_b32 v253, s0, 53
	s_lshl_b32 s0, s82, 8
	v_writelane_b32 v253, s0, 54
	s_add_i32 s0, 0, 0x23fc0
	v_writelane_b32 v253, s0, 55
	s_add_i32 s0, 0, 0x23fc4
	v_writelane_b32 v253, s0, 56
	s_add_i32 s0, 0, 0x20100
	v_writelane_b32 v253, s0, 57
	s_add_i32 s0, 0, 0x20900
	v_writelane_b32 v253, s0, 58
	s_load_dwordx2 s[0:1], s[80:81], 0x80
	s_waitcnt lgkmcnt(0)
	v_writelane_b32 v253, s0, 59
	s_nop 1
	v_writelane_b32 v253, s1, 60
	s_load_dwordx4 s[0:3], s[80:81], 0x70
	s_waitcnt lgkmcnt(0)
	v_writelane_b32 v253, s0, 61
	s_nop 1
	v_writelane_b32 v254, s3, 0
	v_writelane_b32 v254, s78, 1
	v_writelane_b32 v254, s80, 2
	s_mov_b32 s0, s82
	v_writelane_b32 v253, s1, 62
	v_writelane_b32 v254, s81, 3
	v_writelane_b32 v254, s0, 4
	v_writelane_b32 v253, s2, 63
	s_nop 0
	v_writelane_b32 v254, s1, 5
	v_writelane_b32 v254, s86, 6
	s_mov_b32 s0, s84
	s_nop 0
	v_writelane_b32 v254, s87, 7
	v_writelane_b32 v254, s97, 8
	v_writelane_b32 v254, s0, 9
	s_nop 1
	v_writelane_b32 v254, s1, 10
	v_writelane_b32 v254, s88, 11
	s_mov_b32 s0, s96
	s_nop 0
	v_writelane_b32 v254, s89, 12
	v_writelane_b32 v254, s90, 13
	s_nop 1
	v_writelane_b32 v254, s91, 14
	v_writelane_b32 v254, s0, 15
	s_nop 1
	v_writelane_b32 v254, s1, 16
	v_writelane_b32 v254, s79, 17
	v_writelane_b32 v254, s92, 18
	s_mov_b32 s0, s76
	s_nop 0
	v_writelane_b32 v254, s93, 19
	v_writelane_b32 v254, s70, 20
	v_writelane_b32 v254, s71, 21
	v_writelane_b32 v254, s68, 22
	s_nop 1
	v_writelane_b32 v254, s69, 23
	v_writelane_b32 v254, s72, 24
	v_writelane_b32 v254, s73, 25
	v_writelane_b32 v254, s74, 26
	v_writelane_b32 v254, s0, 27
	s_nop 1
	v_writelane_b32 v254, s1, 28
	v_writelane_b32 v254, s34, 29
	v_writelane_b32 v254, s33, 30
	v_writelane_b32 v254, s27, 31
	s_branch .LBB0_238

.LBB0_236:
	s_mov_b32 s101, s100
	s_or_b64 exec, exec, s[0:1]
	s_mov_b64 s[0:1], 0
	s_mov_b64 s[10:11], -1
	s_waitcnt lgkmcnt(0)
	s_barrier

.LBB0_314:
	s_andn2_saveexec_b64 s[4:5], s[4:5]
	s_cbranch_execz .LBB0_334
	s_mov_b64 s[4:5], exec
	s_cmp_eq_u32 s101, 0
	s_cbranch_scc1 .Lgs_nowb_2
	buffer_wbl2 sc1
.Lgs_nowb_2:
	s_waitcnt lgkmcnt(0)
	s_waitcnt vmcnt(0)
	v_mbcnt_lo_u32_b32 v1, s4, 0
	v_mbcnt_hi_u32_b32 v1, s5, v1
	v_cmp_eq_u32_e32 vcc, 0, v1
	s_and_saveexec_b64 s[6:7], vcc
	s_cbranch_execz .LBB0_317
	s_bcnt1_i32_b64 s4, s[4:5]
	v_mov_b32_e32 v2, s4
	v_mov_b32_e32 v3, 0x3000
	global_atomic_add v2, v3, v2, s[2:3] offset:1024 sc0

.LBB0_1405:
	s_andn2_saveexec_b64 s[4:5], s[4:5]
	s_cbranch_execz .LBB0_1425
	s_mov_b64 s[4:5], exec
	s_cmp_eq_u32 s100, 0
	s_cbranch_scc1 .Lgs_nowb_0
	buffer_wbl2 sc1

.LBB0_1494:
	s_mov_b64 s[4:5], exec
	s_cmp_eq_u32 s100, 0
	s_cbranch_scc1 .Lgs_nowb_1
	buffer_wbl2 sc1

	.amdhsa_kernel _Z8mega_fwd4Args
		.amdhsa_group_segment_fixed_size 0
		.amdhsa_private_segment_fixed_size 0
		.amdhsa_kernarg_size 464
		.amdhsa_user_sgpr_count 2
		.amdhsa_user_sgpr_dispatch_ptr 0
		.amdhsa_user_sgpr_queue_ptr 0
		.amdhsa_user_sgpr_kernarg_segment_ptr 1
		.amdhsa_user_sgpr_dispatch_id 0
		.amdhsa_user_sgpr_kernarg_preload_length 0
		.amdhsa_user_sgpr_kernarg_preload_offset 0
		.amdhsa_user_sgpr_private_segment_size 0
		.amdhsa_uses_dynamic_stack 0
		.amdhsa_enable_private_segment 0
		.amdhsa_system_sgpr_workgroup_id_x 1
		.amdhsa_system_sgpr_workgroup_id_y 0
		.amdhsa_system_sgpr_workgroup_id_z 0
		.amdhsa_system_sgpr_workgroup_info 0
		.amdhsa_system_vgpr_workitem_id 2
		.amdhsa_next_free_vgpr 256
		.amdhsa_next_free_sgpr 102
		.amdhsa_accum_offset 256
		.amdhsa_reserve_vcc 1
		.amdhsa_float_round_mode_32 0
		.amdhsa_float_round_mode_16_64 0
		.amdhsa_float_denorm_mode_32 3
		.amdhsa_float_denorm_mode_16_64 3
		.amdhsa_dx10_clamp 1
		.amdhsa_ieee_mode 1
		.amdhsa_fp16_overflow 0
		.amdhsa_tg_split 0
		.amdhsa_exception_fp_ieee_invalid_op 0
		.amdhsa_exception_fp_denorm_src 0
		.amdhsa_exception_fp_ieee_div_zero 0
		.amdhsa_exception_fp_ieee_overflow 0
		.amdhsa_exception_fp_ieee_underflow 0
		.amdhsa_exception_fp_ieee_inexact 0
		.amdhsa_exception_int_div_zero 0
	.end_amdhsa_kernel

amdhsa.kernels:
  - .agpr_count:     0
    .args:
      - .offset:         0
        .size:           208
        .value_kind:     by_value
      - .offset:         208
        .size:           4
        .value_kind:     hidden_block_count_x
      - .offset:         212
        .size:           4
        .value_kind:     hidden_block_count_y
      - .offset:         216
        .size:           4
        .value_kind:     hidden_block_count_z
      - .offset:         220
        .size:           2
        .value_kind:     hidden_group_size_x
      - .offset:         222
        .size:           2
        .value_kind:     hidden_group_size_y
      - .offset:         224
        .size:           2
        .value_kind:     hidden_group_size_z
      - .offset:         226
        .size:           2
        .value_kind:     hidden_remainder_x
      - .offset:         228
        .size:           2
        .value_kind:     hidden_remainder_y
      - .offset:         230
        .size:           2
        .value_kind:     hidden_remainder_z
      - .offset:         248
        .size:           8
        .value_kind:     hidden_global_offset_x
      - .offset:         256
        .size:           8
        .value_kind:     hidden_global_offset_y
      - .offset:         264
        .size:           8
        .value_kind:     hidden_global_offset_z
      - .offset:         272
        .size:           2
        .value_kind:     hidden_grid_dims
      - .offset:         296
        .size:           8
        .value_kind:     hidden_multigrid_sync_arg
      - .offset:         328
        .size:           4
        .value_kind:     hidden_dynamic_lds_size
    .group_segment_fixed_size: 0
    .kernarg_segment_align: 8
    .kernarg_segment_size: 464
    .language:       OpenCL C
    .language_version:
      - 2
      - 0
    .max_flat_workgroup_size: 512
    .name:           _Z8mega_fwd4Args
    .private_segment_fixed_size: 0
    .sgpr_count:     108
    .sgpr_spill_count: 233
    .symbol:         _Z8mega_fwd4Args.kd
    .uniform_work_group_size: 1
    .uses_dynamic_stack: false
    .vgpr_count:     256
    .vgpr_spill_count: 0
    .wavefront_size: 64
